# modulate0 and rope hand-written paths guarded by gridDim == 256 (original loops kept as fallback)
# speedup vs baseline: 1.0006x; 1.0006x over previous
; #define TIDX tid_fn()
; __device__ __forceinline__ void ph_modulate0(const Params& P) {
;   h16* A = (h16*)(P.ws + O_ABUF);
;   const size_t n4 = (size_t)NT * D / 4;
;   for (size_t i = (size_t)blockIdx.x * NTHR + TIDX; i < n4; i += (size_t)gridDim.x * NTHR) {
;     const size_t e = i * 4;
;     const int row = (int)(e / D), k = (int)(e % D);
;     const float* src = row < NL ? P.x + (size_t)row * D : P.ctx + (size_t)(row - NL) * D;
;     const float4 v = *(const float4*)(src + k);
;     const float* sh = mod_ptr(P, 0, row, 0) + k;
;     const float* sc = mod_ptr(P, 0, row, 1) + k;
;     h16x4 o;
;     o[0] = (h16)(v.x * (1.f + sc[0]) + sh[0]); o[1] = (h16)(v.y * (1.f + sc[1]) + sh[1]);
;     o[2] = (h16)(v.z * (1.f + sc[2]) + sh[2]); o[3] = (h16)(v.w * (1.f + sc[3]) + sh[3]);
;     *(h16x4*)(A + e) = o;
;   }
; }
.LBB0_256:
	s_or_b64 exec, exec, s[6:7]
	s_mov_b32 s3, 0
	s_mov_b64 s[4:5], s[96:97]
	s_lshl_b64 s[0:1], s[2:3], 9
	v_mov_b32_e32 v6, v0
	s_waitcnt lgkmcnt(0)
	s_barrier
	v_writelane_b32 v254, s0, 3
	v_ashrrev_i32_e32 v7, 31, v6
	s_nop 0
	v_writelane_b32 v254, s1, 4
	s_load_dword s6, s[96:97], 0x180
	s_waitcnt lgkmcnt(0)
	s_cmp_eq_u32 s6, 0x100
	s_cbranch_scc1 .Lmod0_fast
	v_lshl_add_u64 v[2:3], s[0:1], 0, v[6:7]
	s_mov_b64 s[0:1], 0x1040000
	v_cmp_gt_u64_e32 vcc, s[0:1], v[2:3]
	s_and_saveexec_b64 s[8:9], vcc
	s_cbranch_execz .LBB0_263
	s_load_dword s0, s[96:97], 0x180
	s_load_dwordx2 s[6:7], s[4:5], 0x178
	s_load_dwordx2 s[10:11], s[4:5], 0x0
	s_load_dwordx2 s[12:13], s[4:5], 0x10
	s_mov_b32 s1, s3
	s_waitcnt lgkmcnt(0)
	s_lshl_b64 s[14:15], s[0:1], 9
	s_add_u32 s16, s6, 0x4000
	s_addc_u32 s17, s7, 0
	s_lshl_b64 s[4:5], s[2:3], 12
	s_add_u32 s4, s6, s4
	s_addc_u32 s5, s7, s5
	v_lshl_add_u64 v[4:5], v[6:7], 3, s[4:5]
	s_mov_b64 s[4:5], 0xbe4c000
	v_lshl_add_u64 v[4:5], v[4:5], 0, s[4:5]
	s_lshl_b64 s[4:5], s[2:3], 11
	s_brev_b32 s28, 63
	s_lshl_b64 s[18:19], s[0:1], 12
	v_lshl_add_u64 v[6:7], v[6:7], 2, s[4:5]
	s_lshl_b64 s[20:21], s[0:1], 11
	s_mov_b64 s[22:23], 0
	s_mov_b64 s[24:25], 0x1000000
	s_mov_b64 s[26:27], 0xffffff
	s_movk_i32 s29, 0x7ff
	v_mov_b32_e32 v9, 0
	v_mov_b32_e32 v1, 0x18000
	s_movk_i32 s0, 0x2000
	s_mov_b64 s[30:31], 0x103ffff
	s_branch .LBB0_259

; #define TIDX tid_fn()
; __device__ __forceinline__ void ph_modulate0(const Params& P) {
;   h16* A = (h16*)(P.ws + O_ABUF);
;   const size_t n4 = (size_t)NT * D / 4;
;   for (size_t i = (size_t)blockIdx.x * NTHR + TIDX; i < n4; i += (size_t)gridDim.x * NTHR) {
;     const size_t e = i * 4;
;     const int row = (int)(e / D), k = (int)(e % D);
;     const float* src = row < NL ? P.x + (size_t)row * D : P.ctx + (size_t)(row - NL) * D;
;     const float4 v = *(const float4*)(src + k);
;     const float* sh = mod_ptr(P, 0, row, 0) + k;
;     const float* sc = mod_ptr(P, 0, row, 1) + k;
;     h16x4 o;
;     o[0] = (h16)(v.x * (1.f + sc[0]) + sh[0]); o[1] = (h16)(v.y * (1.f + sc[1]) + sh[1]);
;     o[2] = (h16)(v.z * (1.f + sc[2]) + sh[2]); o[3] = (h16)(v.w * (1.f + sc[3]) + sh[3]);
;     *(h16x4*)(A + e) = o;
;   }
; }
.Lmod0_fast:
	s_mov_b64 s[8:9], exec
	s_load_dwordx2 s[4:5], s[96:97], 0x0
	s_load_dwordx2 s[6:7], s[96:97], 0x10
	s_load_dwordx2 s[14:15], s[96:97], 0x178
	v_lshlrev_b32_e32 v1, 4, v0
	v_lshlrev_b32_e32 v2, 3, v0
	s_waitcnt lgkmcnt(0)
	s_add_u32 s16, s14, 0x4000
	s_addc_u32 s17, s15, 0
	s_add_u32 s18, s14, 0xbe4c000
	s_addc_u32 s19, s15, 0
	s_lshl_b32 s22, s2, 13
	s_add_u32 s10, s4, 0x0
	s_addc_u32 s11, s5, 0
	s_add_u32 s10, s10, s22
	s_addc_u32 s11, s11, 0
	s_lshl_b32 s22, s2, 12
	s_add_u32 s12, s18, 0x0
	s_addc_u32 s13, s19, 0
	s_add_u32 s12, s12, s22
	s_addc_u32 s13, s13, 0
	s_add_u32 s20, s16, 0x0
	s_addc_u32 s21, s17, 0
	global_load_dwordx4 v[8:11], v1, s[20:21]
	s_add_u32 s20, s20, 0x2000
	s_addc_u32 s21, s21, 0
	global_load_dwordx4 v[4:7], v1, s[20:21]
	global_load_dwordx4 v[32:35], v1, s[10:11]
	s_add_u32 s10, s10, 0x200000
	s_addc_u32 s11, s11, 0
	global_load_dwordx4 v[36:39], v1, s[10:11]
	s_add_u32 s10, s10, 0x200000
	s_addc_u32 s11, s11, 0
	global_load_dwordx4 v[40:43], v1, s[10:11]
	s_add_u32 s10, s10, 0x200000
	s_addc_u32 s11, s11, 0
	global_load_dwordx4 v[44:47], v1, s[10:11]
	s_add_u32 s10, s10, 0x200000
	s_addc_u32 s11, s11, 0
	global_load_dwordx4 v[48:51], v1, s[10:11]
	s_add_u32 s10, s10, 0x200000
	s_addc_u32 s11, s11, 0
	global_load_dwordx4 v[52:55], v1, s[10:11]
	s_add_u32 s10, s10, 0x200000
	s_addc_u32 s11, s11, 0
	global_load_dwordx4 v[56:59], v1, s[10:11]
	s_add_u32 s10, s10, 0x200000
	s_addc_u32 s11, s11, 0
	global_load_dwordx4 v[60:63], v1, s[10:11]
	s_add_u32 s10, s10, 0x200000
	s_addc_u32 s11, s11, 0
	s_waitcnt vmcnt(8)
	v_pk_add_f32 v[4:5], v[4:5], 1.0 op_sel_hi:[1,0]
	v_pk_add_f32 v[6:7], v[6:7], 1.0 op_sel_hi:[1,0]
	s_waitcnt vmcnt(7)
	v_pk_fma_f32 v[32:33], v[32:33], v[4:5], v[8:9]
	v_pk_fma_f32 v[34:35], v[34:35], v[6:7], v[10:11]
	v_cvt_pk_f16_f32 v12, v32, v33
	v_cvt_pk_f16_f32 v13, v34, v35
	global_store_dwordx2 v2, v[12:13], s[12:13]
	s_add_u32 s12, s12, 0x100000
	s_addc_u32 s13, s13, 0
	global_load_dwordx4 v[32:35], v1, s[10:11]
	s_add_u32 s10, s10, 0x200000
	s_addc_u32 s11, s11, 0
	s_waitcnt vmcnt(8)
	v_pk_fma_f32 v[36:37], v[36:37], v[4:5], v[8:9]
	v_pk_fma_f32 v[38:39], v[38:39], v[6:7], v[10:11]
	v_cvt_pk_f16_f32 v14, v36, v37
	v_cvt_pk_f16_f32 v15, v38, v39
	global_store_dwordx2 v2, v[14:15], s[12:13]
	s_add_u32 s12, s12, 0x100000
	s_addc_u32 s13, s13, 0
	global_load_dwordx4 v[36:39], v1, s[10:11]
	s_add_u32 s10, s10, 0x200000
	s_addc_u32 s11, s11, 0
	s_waitcnt vmcnt(9)
	v_pk_fma_f32 v[40:41], v[40:41], v[4:5], v[8:9]
	v_pk_fma_f32 v[42:43], v[42:43], v[6:7], v[10:11]
	v_cvt_pk_f16_f32 v16, v40, v41
	v_cvt_pk_f16_f32 v17, v42, v43
	global_store_dwordx2 v2, v[16:17], s[12:13]
	s_add_u32 s12, s12, 0x100000
	s_addc_u32 s13, s13, 0
	global_load_dwordx4 v[40:43], v1, s[10:11]
	s_add_u32 s10, s10, 0x200000
	s_addc_u32 s11, s11, 0
	s_waitcnt vmcnt(10)
	v_pk_fma_f32 v[44:45], v[44:45], v[4:5], v[8:9]
	v_pk_fma_f32 v[46:47], v[46:47], v[6:7], v[10:11]
	v_cvt_pk_f16_f32 v18, v44, v45
	v_cvt_pk_f16_f32 v19, v46, v47
	global_store_dwordx2 v2, v[18:19], s[12:13]
	s_add_u32 s12, s12, 0x100000
	s_addc_u32 s13, s13, 0
	global_load_dwordx4 v[44:47], v1, s[10:11]
	s_add_u32 s10, s10, 0x200000
	s_addc_u32 s11, s11, 0
	s_waitcnt vmcnt(11)
	v_pk_fma_f32 v[48:49], v[48:49], v[4:5], v[8:9]
	v_pk_fma_f32 v[50:51], v[50:51], v[6:7], v[10:11]
	v_cvt_pk_f16_f32 v12, v48, v49
	v_cvt_pk_f16_f32 v13, v50, v51
	global_store_dwordx2 v2, v[12:13], s[12:13]
	s_add_u32 s12, s12, 0x100000
	s_addc_u32 s13, s13, 0
	global_load_dwordx4 v[48:51], v1, s[10:11]
	s_add_u32 s10, s10, 0x200000
	s_addc_u32 s11, s11, 0
	s_waitcnt vmcnt(12)
	v_pk_fma_f32 v[52:53], v[52:53], v[4:5], v[8:9]
	v_pk_fma_f32 v[54:55], v[54:55], v[6:7], v[10:11]
	v_cvt_pk_f16_f32 v14, v52, v53
	v_cvt_pk_f16_f32 v15, v54, v55
	global_store_dwordx2 v2, v[14:15], s[12:13]
	s_add_u32 s12, s12, 0x100000
	s_addc_u32 s13, s13, 0
	global_load_dwordx4 v[52:55], v1, s[10:11]
	s_add_u32 s10, s10, 0x200000
	s_addc_u32 s11, s11, 0
	s_waitcnt vmcnt(13)
	v_pk_fma_f32 v[56:57], v[56:57], v[4:5], v[8:9]
	v_pk_fma_f32 v[58:59], v[58:59], v[6:7], v[10:11]
	v_cvt_pk_f16_f32 v16, v56, v57
	v_cvt_pk_f16_f32 v17, v58, v59
	global_store_dwordx2 v2, v[16:17], s[12:13]
	s_add_u32 s12, s12, 0x100000
	s_addc_u32 s13, s13, 0
	global_load_dwordx4 v[56:59], v1, s[10:11]
	s_add_u32 s10, s10, 0x200000
	s_addc_u32 s11, s11, 0
	s_waitcnt vmcnt(14)
	v_pk_fma_f32 v[60:61], v[60:61], v[4:5], v[8:9]
	v_pk_fma_f32 v[62:63], v[62:63], v[6:7], v[10:11]
	v_cvt_pk_f16_f32 v18, v60, v61
	v_cvt_pk_f16_f32 v19, v62, v63
	global_store_dwordx2 v2, v[18:19], s[12:13]
	s_add_u32 s12, s12, 0x100000
	s_addc_u32 s13, s13, 0
	global_load_dwordx4 v[60:63], v1, s[10:11]
	s_add_u32 s10, s10, 0x200000
	s_addc_u32 s11, s11, 0
	s_mov_b32 s23, 6

; #define TIDX tid_fn()
; __device__ __forceinline__ void ph_rope(const Params& P) {
;     ...
;   const size_t total = (size_t)NT * PER_ROW;
; #pragma unroll 2
;   for (size_t i = (size_t)blockIdx.x * NTHR + TIDX; i < total; i += (size_t)gridDim.x * NTHR) {
;     const int row = (int)(i / PER_ROW), it = (int)(i % PER_ROW);
;     const int f4 = it % 16, hh = (it / 16) % RET_HEADS, qk = it / (16 * RET_HEADS);
;     int isc, b, t; row_decode(row, isc, b, t);
.LBB0_522:
	s_cmp_eq_u32 s84, 0x100
	s_cbranch_scc1 .Lrope_fast
	s_mov_b64 s[6:7], s[96:97]
	v_mov_b32_e32 v6, v0
	v_readlane_b32 s0, v254, 3
	v_readlane_b32 s1, v254, 4
	v_ashrrev_i32_e32 v7, 31, v6
	s_mov_b64 s[4:5], 0x820000
	v_lshl_add_u64 v[2:3], s[0:1], 0, v[6:7]
	v_cmp_gt_u64_e32 vcc, s[4:5], v[2:3]
	s_and_saveexec_b64 s[8:9], vcc
	s_cbranch_execz .LBB0_532
	s_mov_b32 s85, 0
	s_lshl_b64 s[10:11], s[84:85], 9
	v_lshl_add_u64 v[4:5], v[2:3], 0, s[10:11]
	v_cmp_lt_u64_e32 vcc, s[4:5], v[4:5]
	v_mov_b32_e32 v1, 0x820000
	v_mov_b32_e32 v9, s85
	v_cndmask_b32_e32 v7, 0, v5, vcc
	v_cndmask_b32_e32 v1, v1, v4, vcc
	v_cmp_gt_u64_e32 vcc, s[4:5], v[4:5]
	s_load_dwordx2 s[14:15], s[6:7], 0x178
	s_nop 0
	v_cndmask_b32_e64 v8, 0, 1, vcc
	v_lshl_add_u64 v[10:11], v[4:5], 0, v[8:9]
	v_sub_co_u32_e32 v1, vcc, v1, v10
	v_mov_b32_e32 v10, 0
	s_nop 0
	v_subb_co_u32_e32 v7, vcc, v7, v11, vcc
	v_or_b32_e32 v11, s11, v7
	v_cmp_ne_u64_e32 vcc, 0, v[10:11]
	s_and_saveexec_b64 s[0:1], vcc
	s_xor_b64 s[12:13], exec, s[0:1]
	s_cbranch_execz .LBB0_525
	v_cvt_f32_u32_e32 v11, s10
	v_cvt_f32_u32_e32 v12, s11
	s_sub_u32 s4, 0, s10
	s_subb_u32 s5, 0, s11
	v_mov_b32_e32 v15, v10
	v_fmamk_f32 v11, v12, 0x4f800000, v11
	v_rcp_f32_e32 v11, v11
	s_nop 0
	v_mul_f32_e32 v11, 0x5f7ffffc, v11
	v_mul_f32_e32 v12, 0x2f800000, v11
	v_trunc_f32_e32 v12, v12
	v_fmamk_f32 v11, v12, 0xcf800000, v11
	v_cvt_u32_f32_e32 v12, v12
	v_cvt_u32_f32_e32 v11, v11
	v_readfirstlane_b32 s6, v12
	v_readfirstlane_b32 s0, v11
	s_mul_i32 s1, s4, s6
	s_mul_hi_u32 s16, s4, s0
	s_mul_i32 s7, s5, s0
	s_add_i32 s1, s16, s1
	s_mul_i32 s17, s4, s0
	s_add_i32 s1, s1, s7
	s_mul_i32 s16, s0, s1
	s_mul_hi_u32 s18, s0, s17
	s_mul_hi_u32 s7, s0, s1
	s_add_u32 s16, s18, s16
	s_addc_u32 s7, 0, s7
	s_mul_hi_u32 s19, s6, s17
	s_mul_i32 s17, s6, s17
	s_add_u32 s16, s16, s17
	s_mul_hi_u32 s18, s6, s1
	s_addc_u32 s7, s7, s19
	s_addc_u32 s16, s18, 0
	s_mul_i32 s1, s6, s1
	s_add_u32 s1, s7, s1
	s_addc_u32 s7, 0, s16
	s_add_u32 s16, s0, s1
	s_cselect_b64 s[0:1], -1, 0
	s_cmp_lg_u64 s[0:1], 0
	s_addc_u32 s6, s6, s7
	s_mul_i32 s0, s4, s6
	s_mul_hi_u32 s1, s4, s16
	s_add_i32 s0, s1, s0
	s_mul_i32 s5, s5, s16
	s_add_i32 s0, s0, s5
	s_mul_i32 s4, s4, s16
	s_mul_hi_u32 s5, s6, s4
	s_mul_i32 s7, s6, s4
	s_mul_i32 s18, s16, s0
	s_mul_hi_u32 s4, s16, s4
	s_mul_hi_u32 s17, s16, s0
	s_add_u32 s4, s4, s18
	s_addc_u32 s17, 0, s17
	s_add_u32 s4, s4, s7
	s_mul_hi_u32 s1, s6, s0
	s_addc_u32 s4, s17, s5
	s_addc_u32 s1, s1, 0
	s_mul_i32 s0, s6, s0
	s_add_u32 s0, s4, s0
	s_addc_u32 s4, 0, s1
	s_add_u32 s5, s16, s0
	s_cselect_b64 s[0:1], -1, 0
	s_cmp_lg_u64 s[0:1], 0
	s_addc_u32 s4, s6, s4
	v_mad_u64_u32 v[12:13], s[0:1], v1, s4, 0
	v_mul_hi_u32 v14, v1, s5
	v_lshl_add_u64 v[12:13], v[14:15], 0, v[12:13]
	v_mad_u64_u32 v[16:17], s[0:1], v7, s5, 0
	v_add_co_u32_e32 v11, vcc, v12, v16
	v_mad_u64_u32 v[14:15], s[0:1], v7, s4, 0
	s_nop 0
	v_addc_co_u32_e32 v12, vcc, v13, v17, vcc
	v_mov_b32_e32 v13, v10
	s_nop 0
	v_addc_co_u32_e32 v15, vcc, 0, v15, vcc
	v_lshl_add_u64 v[10:11], v[12:13], 0, v[14:15]
	v_mul_lo_u32 v14, s11, v10
	v_mul_lo_u32 v15, s10, v11
	v_mad_u64_u32 v[12:13], s[0:1], s10, v10, 0
	v_add3_u32 v16, v13, v15, v14
	v_sub_u32_e32 v13, v7, v16
	v_mov_b32_e32 v14, s11
	v_sub_co_u32_e32 v1, vcc, v1, v12
	s_nop 1
	v_subb_co_u32_e64 v12, s[6:7], v13, v14, vcc
	v_subrev_co_u32_e64 v13, s[6:7], s10, v1
	v_subb_co_u32_e32 v7, vcc, v7, v16, vcc
	s_nop 0
	v_subbrev_co_u32_e64 v12, s[6:7], 0, v12, s[6:7]
	v_cmp_le_u32_e64 s[6:7], s11, v12
	v_cmp_le_u32_e32 vcc, s11, v7
	s_nop 0
	v_cndmask_b32_e64 v14, 0, -1, s[6:7]
	v_cmp_le_u32_e64 s[6:7], s10, v13
	s_nop 1
	v_cndmask_b32_e64 v13, 0, -1, s[6:7]
	v_cmp_eq_u32_e64 s[6:7], s11, v12
	s_nop 1
	v_cndmask_b32_e64 v17, v14, v13, s[6:7]
	v_lshl_add_u64 v[12:13], v[10:11], 0, 2
	v_lshl_add_u64 v[14:15], v[10:11], 0, 1
	v_cmp_ne_u32_e64 s[6:7], 0, v17
	s_nop 1
	v_cndmask_b32_e64 v13, v15, v13, s[6:7]
	v_cndmask_b32_e64 v15, 0, -1, vcc
	v_cmp_le_u32_e32 vcc, s10, v1
	s_nop 1
	v_cndmask_b32_e64 v1, 0, -1, vcc
	v_cmp_eq_u32_e32 vcc, s11, v7
	s_nop 1
	v_cndmask_b32_e32 v1, v15, v1, vcc
	v_cmp_ne_u32_e32 vcc, 0, v1
	v_cndmask_b32_e64 v1, v14, v12, s[6:7]
	s_nop 0
	v_cndmask_b32_e32 v13, v11, v13, vcc
	v_cndmask_b32_e32 v12, v10, v1, vcc

; #define TIDX tid_fn()
; __device__ __forceinline__ void ph_rope(const Params& P) {
;     ...
;   for (size_t i = (size_t)blockIdx.x * NTHR + TIDX; i < total; i += (size_t)gridDim.x * NTHR) {
;     const int row = (int)(i / PER_ROW), it = (int)(i % PER_ROW);
;     const int f4 = it % 16, hh = (it / 16) % RET_HEADS, qk = it / (16 * RET_HEADS);
;     int isc, b, t; row_decode(row, isc, b, t);
;     const int pos = isc ? SEQ + t : t;
;     h16* pr = p + (size_t)row * NP_EV + 3 * HY_CH + qk * RETW + hh * RET_HD + f4 * 4;
;     const h16x4 t1 = *(const h16x4*)pr, t2 = *(const h16x4*)(pr + 64);
;     const float4 c = *(const float4*)(rc + (size_t)pos * 64 + f4 * 4), s = *(const float4*)(rs + (size_t)pos * 64 + f4 * 4);
;     const float sc = qk ? kscale : 1.0f;
;     h16x4 o1, o2;
;     o1[0] = (h16)(((float)t1[0] * c.x - (float)t2[0] * s.x) * sc); o2[0] = (h16)(((float)t1[0] * s.x + (float)t2[0] * c.x) * sc);
;     o1[1] = (h16)(((float)t1[1] * c.y - (float)t2[1] * s.y) * sc); o2[1] = (h16)(((float)t1[1] * s.y + (float)t2[1] * c.y) * sc);
;     o1[2] = (h16)(((float)t1[2] * c.z - (float)t2[2] * s.z) * sc); o2[2] = (h16)(((float)t1[2] * s.z + (float)t2[2] * c.z) * sc);
;     o1[3] = (h16)(((float)t1[3] * c.w - (float)t2[3] * s.w) * sc); o2[3] = (h16)(((float)t1[3] * s.w + (float)t2[3] * c.w) * sc);
;     *(h16x4*)pr = o1; *(h16x4*)(pr + 64) = o2;
;   }
.LBB0_531:
	v_lshrrev_b64 v[12:13], 8, v[2:3]
	v_alignbit_b32 v10, v3, v2, 8
	v_bfe_u32 v32, v2, 7, 1
	v_lshrrev_b32_e32 v13, 8, v3
	v_add_u32_e32 v24, 0xffffc000, v10
	v_mad_u64_u32 v[22:23], s[30:31], v10, s1, v[8:9]
	v_cmp_gt_u64_e32 vcc, s[26:27], v[2:3]
	v_and_b32_e32 v14, 0x380, v6
	v_and_b32_e32 v19, 60, v4
	v_or_b32_sdwa v25, v10, s0 dst_sel:DWORD dst_unused:UNUSED_PAD src0_sel:BYTE_0 src1_sel:DWORD
	v_lshlrev_b32_e32 v10, 11, v32
	v_cndmask_b32_e32 v12, v24, v12, vcc
	v_mad_u32_u24 v23, v13, s1, v23
	v_cmp_gt_u64_e32 vcc, s[24:25], v[2:3]
	v_mov_b32_e32 v15, v11
	v_lshlrev_b32_e32 v14, 1, v14
	v_lshlrev_b32_e32 v16, 1, v19
	v_lshlrev_b32_e32 v20, 2, v19
	v_cndmask_b32_e32 v19, v25, v12, vcc
	v_lshl_add_u64 v[12:13], v[22:23], 0, v[10:11]
	v_mov_b32_e32 v17, v11
	v_lshl_add_u64 v[12:13], v[12:13], 0, v[14:15]
	v_mov_b32_e32 v18, v11
	v_lshl_add_u64 v[12:13], v[12:13], 0, v[16:17]
	v_ashrrev_i64 v[14:15], 24, v[18:19]
	v_add_co_u32_e32 v24, vcc, s4, v12
	v_mov_b32_e32 v21, v11
	v_lshl_add_u64 v[16:17], s[6:7], 0, v[14:15]
	v_lshl_add_u64 v[14:15], s[12:13], 0, v[14:15]
	v_addc_co_u32_e32 v25, vcc, 0, v13, vcc
	v_lshl_add_u64 v[22:23], v[12:13], 0, s[14:15]
	v_lshl_add_u64 v[26:27], v[16:17], 0, v[20:21]
	v_lshl_add_u64 v[20:21], v[14:15], 0, v[20:21]
	global_load_dwordx2 v[28:29], v[24:25], off offset:2048
	global_load_dwordx2 v[30:31], v[22:23], off offset:128
	global_load_dwordx4 v[12:15], v[20:21], off
	global_load_dwordx4 v[16:19], v[26:27], off
	v_lshl_add_u64 v[2:3], v[2:3], 0, s[10:11]
	v_cmp_eq_u32_e32 vcc, 0, v32
	v_lshrrev_b64 v[32:33], 8, v[2:3]
	v_add_u32_e32 v21, s18, v6
	v_alignbit_b32 v33, v3, v2, 8
	v_cndmask_b32_e64 v26, v1, 1.0, vcc
	v_and_b32_e32 v37, 0x380, v21
	v_add_u32_e32 v21, 0xffffc000, v33
	v_cmp_gt_u64_e32 vcc, s[26:27], v[2:3]
	v_or_b32_sdwa v38, v33, s0 dst_sel:DWORD dst_unused:UNUSED_PAD src0_sel:BYTE_0 src1_sel:DWORD
	v_lshrrev_b32_e32 v36, 8, v3
	v_cndmask_b32_e32 v21, v21, v32, vcc
	v_cmp_gt_u64_e32 vcc, s[24:25], v[2:3]
	v_mad_u64_u32 v[34:35], s[30:31], v33, s1, v[8:9]
	s_nop 0
	v_cndmask_b32_e32 v21, v38, v21, vcc
	v_add_u32_e32 v27, s16, v4
	v_mad_u32_u24 v35, v36, s1, v35
	v_and_b32_e32 v27, 60, v27
	v_lshl_add_u64 v[32:33], v[34:35], 0, v[10:11]
	v_lshlrev_b32_e32 v10, 1, v37
	v_lshl_add_u64 v[32:33], v[32:33], 0, v[10:11]
	v_lshlrev_b32_e32 v10, 1, v27
	v_mov_b32_e32 v20, v11
	v_lshl_add_u64 v[32:33], v[32:33], 0, v[10:11]
	v_ashrrev_i64 v[20:21], 24, v[20:21]
	v_lshl_add_u64 v[36:37], v[32:33], 0, s[14:15]
	v_add_co_u32_e32 v32, vcc, s4, v32
	v_lshl_add_u64 v[34:35], s[6:7], 0, v[20:21]
	v_lshlrev_b32_e32 v10, 2, v27
	v_lshl_add_u64 v[20:21], s[12:13], 0, v[20:21]
	v_addc_co_u32_e32 v33, vcc, 0, v33, vcc
	v_lshl_add_u64 v[34:35], v[34:35], 0, v[10:11]
	v_lshl_add_u64 v[20:21], v[20:21], 0, v[10:11]
	v_lshl_add_u64 v[2:3], v[2:3], 0, s[10:11]
	v_cmp_lt_u64_e32 vcc, s[28:29], v[2:3]
	v_lshl_add_u64 v[4:5], v[4:5], 0, s[18:19]
	v_lshl_add_u64 v[6:7], v[6:7], 0, s[20:21]
	s_or_b64 s[22:23], vcc, s[22:23]
	s_waitcnt vmcnt(3)
	v_cvt_f32_f16_e32 v38, v28
	v_cvt_f32_f16_sdwa v39, v28 dst_sel:DWORD dst_unused:UNUSED_PAD src0_sel:WORD_1
	s_waitcnt vmcnt(2)
	v_cvt_f32_f16_e32 v40, v30
	v_cvt_f32_f16_sdwa v41, v30 dst_sel:DWORD dst_unused:UNUSED_PAD src0_sel:WORD_1
	v_cvt_f32_f16_e32 v28, v29
	v_cvt_f32_f16_sdwa v29, v29 dst_sel:DWORD dst_unused:UNUSED_PAD src0_sel:WORD_1
	v_cvt_f32_f16_e32 v30, v31
	v_cvt_f32_f16_sdwa v31, v31 dst_sel:DWORD dst_unused:UNUSED_PAD src0_sel:WORD_1
	s_waitcnt vmcnt(1)
	v_pk_mul_f32 v[42:43], v[12:13], v[38:39]
	v_pk_mul_f32 v[12:13], v[12:13], v[40:41]
	v_pk_mul_f32 v[44:45], v[14:15], v[28:29]
	v_pk_mul_f32 v[14:15], v[14:15], v[30:31]
	s_waitcnt vmcnt(0)
	v_pk_fma_f32 v[12:13], v[16:17], v[38:39], v[12:13] neg_lo:[0,0,1] neg_hi:[0,0,1]
	v_pk_fma_f32 v[14:15], v[18:19], v[28:29], v[14:15] neg_lo:[0,0,1] neg_hi:[0,0,1]
	v_pk_fma_f32 v[40:41], v[16:17], v[40:41], v[42:43]
	v_pk_fma_f32 v[16:17], v[18:19], v[30:31], v[44:45]
	v_pk_mul_f32 v[12:13], v[26:27], v[12:13] op_sel_hi:[0,1]
	v_pk_mul_f32 v[14:15], v[26:27], v[14:15] op_sel_hi:[0,1]
	v_pk_mul_f32 v[18:19], v[26:27], v[40:41] op_sel_hi:[0,1]
	v_pk_mul_f32 v[16:17], v[26:27], v[16:17] op_sel_hi:[0,1]
	v_cvt_pk_f16_f32 v12, v12, v13
	v_cvt_pk_f16_f32 v13, v14, v15
	v_cvt_pk_f16_f32 v18, v18, v19
	v_cvt_pk_f16_f32 v19, v16, v17
	global_store_dwordx2 v[24:25], v[12:13], off offset:2048
	global_store_dwordx2 v[22:23], v[18:19], off offset:128
	global_load_dwordx2 v[22:23], v[32:33], off offset:2048
	s_nop 0
	global_load_dwordx2 v[24:25], v[36:37], off offset:128
	global_load_dwordx4 v[12:15], v[20:21], off
	global_load_dwordx4 v[16:19], v[34:35], off
	s_waitcnt vmcnt(3)
	v_cvt_f32_f16_e32 v20, v22
	v_cvt_f32_f16_sdwa v21, v22 dst_sel:DWORD dst_unused:UNUSED_PAD src0_sel:WORD_1
	s_waitcnt vmcnt(2)
	v_cvt_f32_f16_e32 v28, v24
	v_cvt_f32_f16_sdwa v29, v24 dst_sel:DWORD dst_unused:UNUSED_PAD src0_sel:WORD_1
	v_cvt_f32_f16_e32 v22, v23
	v_cvt_f32_f16_sdwa v23, v23 dst_sel:DWORD dst_unused:UNUSED_PAD src0_sel:WORD_1
	v_cvt_f32_f16_e32 v24, v25
	v_cvt_f32_f16_sdwa v25, v25 dst_sel:DWORD dst_unused:UNUSED_PAD src0_sel:WORD_1
	s_waitcnt vmcnt(1)
	v_pk_mul_f32 v[30:31], v[12:13], v[20:21]
	v_pk_mul_f32 v[12:13], v[12:13], v[28:29]
	v_pk_mul_f32 v[34:35], v[14:15], v[22:23]
	v_pk_mul_f32 v[14:15], v[14:15], v[24:25]
	s_waitcnt vmcnt(0)
	v_pk_fma_f32 v[12:13], v[16:17], v[20:21], v[12:13] neg_lo:[0,0,1] neg_hi:[0,0,1]
	v_pk_fma_f32 v[14:15], v[18:19], v[22:23], v[14:15] neg_lo:[0,0,1] neg_hi:[0,0,1]
	v_pk_fma_f32 v[28:29], v[16:17], v[28:29], v[30:31]
	v_pk_fma_f32 v[16:17], v[18:19], v[24:25], v[34:35]
	v_pk_mul_f32 v[12:13], v[26:27], v[12:13] op_sel_hi:[0,1]
	v_pk_mul_f32 v[14:15], v[26:27], v[14:15] op_sel_hi:[0,1]
	v_pk_mul_f32 v[18:19], v[26:27], v[28:29] op_sel_hi:[0,1]
	v_pk_mul_f32 v[16:17], v[26:27], v[16:17] op_sel_hi:[0,1]
	v_cvt_pk_f16_f32 v12, v12, v13
	v_cvt_pk_f16_f32 v13, v14, v15
	v_cvt_pk_f16_f32 v18, v18, v19
	v_cvt_pk_f16_f32 v19, v16, v17
	global_store_dwordx2 v[32:33], v[12:13], off offset:2048
	global_store_dwordx2 v[36:37], v[18:19], off offset:128
	s_andn2_b64 exec, exec, s[22:23]
	s_cbranch_execnz .LBB0_531
	s_branch .LBB0_532
